# G4 residual epilogue rewritten by hand: 16 residual loads issued up front, counted vmcnt, atomics batched at end (on top of G3 epilogue load hoist)
# speedup vs baseline: 1.0029x; 1.0015x over previous
.LBB0_1047:
	v_lshl_add_u32 v154, s54, 8, v146
	v_lshl_or_b32 v145, s51, 8, v148
	v_lshl_add_u32 v144, v154, 10, v145
	v_lshlrev_b32_e32 v144, 1, v144
	v_mov_b32_e32 v145, v144
	v_lshlrev_b32_e32 v154, 2, v154
	global_load_dwordx4 v[140:143], v144, s[6:7]
	global_load_dwordx4 v[150:153], v144, s[6:7] offset:256
	v_add_u32_e32 v144, 0x8000, v144
	global_load_dwordx4 v[172:175], v144, s[6:7]
	global_load_dwordx4 v[176:179], v144, s[6:7] offset:256
	v_add_u32_e32 v144, 0x8000, v144
	global_load_dwordx4 v[180:183], v144, s[6:7]
	global_load_dwordx4 v[184:187], v144, s[6:7] offset:256
	v_add_u32_e32 v144, 0x8000, v144
	global_load_dwordx4 v[188:191], v144, s[6:7]
	global_load_dwordx4 v[200:203], v144, s[6:7] offset:256
	v_add_u32_e32 v144, 0x28000, v144
	global_load_dwordx4 v[204:207], v144, s[6:7]
	global_load_dwordx4 v[208:211], v144, s[6:7] offset:256
	v_add_u32_e32 v144, 0x8000, v144
	global_load_dwordx4 v[212:215], v144, s[6:7]
	global_load_dwordx4 v[216:219], v144, s[6:7] offset:256
	v_add_u32_e32 v144, 0x8000, v144
	global_load_dwordx4 v[220:223], v144, s[6:7]
	global_load_dwordx4 v[224:227], v144, s[6:7] offset:256
	v_add_u32_e32 v144, 0x8000, v144
	global_load_dwordx4 v[228:231], v144, s[6:7]
	global_load_dwordx4 v[232:235], v144, s[6:7] offset:256
	v_xor_b32_e32 v155, 16, v197
	v_xor_b32_e32 v192, 32, v197
	v_lshlrev_b32_e32 v155, 2, v155
	v_lshlrev_b32_e32 v192, 2, v192
	s_waitcnt vmcnt(14)
	v_lshlrev_b32_e32 v236, 16, v140
	v_and_b32_e32 v237, 0xffff0000, v140
	v_lshlrev_b32_e32 v238, 16, v141
	v_and_b32_e32 v239, 0xffff0000, v141
	v_lshlrev_b32_e32 v140, 16, v142
	v_and_b32_e32 v141, 0xffff0000, v142
	v_lshlrev_b32_e32 v142, 16, v143
	v_and_b32_e32 v143, 0xffff0000, v143
	v_pk_add_f32 v[128:129], v[128:129], v[236:237]
	v_pk_add_f32 v[130:131], v[130:131], v[238:239]
	v_pk_add_f32 v[124:125], v[124:125], v[140:141]
	v_pk_add_f32 v[126:127], v[126:127], v[142:143]
	v_cvt_pk_bf16_f32 v140, v128, v129
	v_cvt_pk_bf16_f32 v141, v130, v131
	v_cvt_pk_bf16_f32 v142, v124, v125
	v_cvt_pk_bf16_f32 v143, v126, v127
	global_store_dwordx4 v145, v[140:143], s[6:7]
	v_pk_mul_f32 v[128:129], v[128:129], v[128:129]
	v_pk_mul_f32 v[130:131], v[130:131], v[130:131]
	v_pk_fma_f32 v[128:129], v[124:125], v[124:125], v[128:129]
	v_pk_fma_f32 v[130:131], v[126:127], v[126:127], v[130:131]
	v_lshlrev_b32_e32 v236, 16, v150
	v_and_b32_e32 v237, 0xffff0000, v150
	v_lshlrev_b32_e32 v238, 16, v151
	v_and_b32_e32 v239, 0xffff0000, v151
	v_lshlrev_b32_e32 v150, 16, v152
	v_and_b32_e32 v151, 0xffff0000, v152
	v_lshlrev_b32_e32 v152, 16, v153
	v_and_b32_e32 v153, 0xffff0000, v153
	v_pk_add_f32 v[120:121], v[120:121], v[236:237]
	v_pk_add_f32 v[122:123], v[122:123], v[238:239]
	v_pk_add_f32 v[116:117], v[116:117], v[150:151]
	v_pk_add_f32 v[118:119], v[118:119], v[152:153]
	v_cvt_pk_bf16_f32 v150, v120, v121
	v_cvt_pk_bf16_f32 v151, v122, v123
	v_cvt_pk_bf16_f32 v152, v116, v117
	v_cvt_pk_bf16_f32 v153, v118, v119
	global_store_dwordx4 v145, v[150:153], s[6:7] offset:256
	v_pk_fma_f32 v[128:129], v[120:121], v[120:121], v[128:129]
	v_pk_fma_f32 v[130:131], v[122:123], v[122:123], v[130:131]
	v_pk_fma_f32 v[128:129], v[116:117], v[116:117], v[128:129]
	v_pk_fma_f32 v[130:131], v[118:119], v[118:119], v[130:131]
	v_add_u32_e32 v145, 0x8000, v145
	v_add_f32_e32 v128, v128, v129
	v_add_f32_e32 v130, v130, v131
	v_add_f32_e32 v128, v128, v130
	s_waitcnt vmcnt(14)
	v_lshlrev_b32_e32 v236, 16, v172
	v_and_b32_e32 v237, 0xffff0000, v172
	v_lshlrev_b32_e32 v238, 16, v173
	v_and_b32_e32 v239, 0xffff0000, v173
	v_lshlrev_b32_e32 v172, 16, v174
	v_and_b32_e32 v173, 0xffff0000, v174
	v_lshlrev_b32_e32 v174, 16, v175
	v_and_b32_e32 v175, 0xffff0000, v175
	v_pk_add_f32 v[112:113], v[112:113], v[236:237]
	v_pk_add_f32 v[114:115], v[114:115], v[238:239]
	v_pk_add_f32 v[108:109], v[108:109], v[172:173]
	v_pk_add_f32 v[110:111], v[110:111], v[174:175]
	v_cvt_pk_bf16_f32 v172, v112, v113
	v_cvt_pk_bf16_f32 v173, v114, v115
	v_cvt_pk_bf16_f32 v174, v108, v109
	v_cvt_pk_bf16_f32 v175, v110, v111
	global_store_dwordx4 v145, v[172:175], s[6:7]
	v_pk_mul_f32 v[112:113], v[112:113], v[112:113]
	v_pk_mul_f32 v[114:115], v[114:115], v[114:115]
	v_pk_fma_f32 v[112:113], v[108:109], v[108:109], v[112:113]
	v_pk_fma_f32 v[114:115], v[110:111], v[110:111], v[114:115]
	v_lshlrev_b32_e32 v236, 16, v176
	v_and_b32_e32 v237, 0xffff0000, v176
	v_lshlrev_b32_e32 v238, 16, v177
	v_and_b32_e32 v239, 0xffff0000, v177
	v_lshlrev_b32_e32 v176, 16, v178
	v_and_b32_e32 v177, 0xffff0000, v178
	v_lshlrev_b32_e32 v178, 16, v179
	v_and_b32_e32 v179, 0xffff0000, v179
	v_pk_add_f32 v[104:105], v[104:105], v[236:237]
	v_pk_add_f32 v[106:107], v[106:107], v[238:239]
	v_pk_add_f32 v[100:101], v[100:101], v[176:177]
	v_pk_add_f32 v[102:103], v[102:103], v[178:179]
	v_cvt_pk_bf16_f32 v176, v104, v105
	v_cvt_pk_bf16_f32 v177, v106, v107
	v_cvt_pk_bf16_f32 v178, v100, v101
	v_cvt_pk_bf16_f32 v179, v102, v103
	global_store_dwordx4 v145, v[176:179], s[6:7] offset:256
	v_pk_fma_f32 v[112:113], v[104:105], v[104:105], v[112:113]
	v_pk_fma_f32 v[114:115], v[106:107], v[106:107], v[114:115]
	v_pk_fma_f32 v[112:113], v[100:101], v[100:101], v[112:113]
	v_pk_fma_f32 v[114:115], v[102:103], v[102:103], v[114:115]
	v_add_u32_e32 v145, 0x8000, v145
	v_add_f32_e32 v112, v112, v113
	v_add_f32_e32 v114, v114, v115
	v_add_f32_e32 v112, v112, v114
	s_waitcnt vmcnt(14)
	v_lshlrev_b32_e32 v236, 16, v180
	v_and_b32_e32 v237, 0xffff0000, v180
	v_lshlrev_b32_e32 v238, 16, v181
	v_and_b32_e32 v239, 0xffff0000, v181
	v_lshlrev_b32_e32 v180, 16, v182
	v_and_b32_e32 v181, 0xffff0000, v182
	v_lshlrev_b32_e32 v182, 16, v183
	v_and_b32_e32 v183, 0xffff0000, v183
	v_pk_add_f32 v[96:97], v[96:97], v[236:237]
	v_pk_add_f32 v[98:99], v[98:99], v[238:239]
	v_pk_add_f32 v[92:93], v[92:93], v[180:181]
	v_pk_add_f32 v[94:95], v[94:95], v[182:183]
	v_cvt_pk_bf16_f32 v180, v96, v97
	v_cvt_pk_bf16_f32 v181, v98, v99
	v_cvt_pk_bf16_f32 v182, v92, v93
	v_cvt_pk_bf16_f32 v183, v94, v95
	global_store_dwordx4 v145, v[180:183], s[6:7]
	v_pk_mul_f32 v[96:97], v[96:97], v[96:97]
	v_pk_mul_f32 v[98:99], v[98:99], v[98:99]
	v_pk_fma_f32 v[96:97], v[92:93], v[92:93], v[96:97]
	v_pk_fma_f32 v[98:99], v[94:95], v[94:95], v[98:99]
	v_lshlrev_b32_e32 v236, 16, v184
	v_and_b32_e32 v237, 0xffff0000, v184
	v_lshlrev_b32_e32 v238, 16, v185
	v_and_b32_e32 v239, 0xffff0000, v185
	v_lshlrev_b32_e32 v184, 16, v186
	v_and_b32_e32 v185, 0xffff0000, v186
	v_lshlrev_b32_e32 v186, 16, v187
	v_and_b32_e32 v187, 0xffff0000, v187
	v_pk_add_f32 v[88:89], v[88:89], v[236:237]
	v_pk_add_f32 v[90:91], v[90:91], v[238:239]
	v_pk_add_f32 v[84:85], v[84:85], v[184:185]
	v_pk_add_f32 v[86:87], v[86:87], v[186:187]
	v_cvt_pk_bf16_f32 v184, v88, v89
	v_cvt_pk_bf16_f32 v185, v90, v91
	v_cvt_pk_bf16_f32 v186, v84, v85
	v_cvt_pk_bf16_f32 v187, v86, v87
	global_store_dwordx4 v145, v[184:187], s[6:7] offset:256
	v_pk_fma_f32 v[96:97], v[88:89], v[88:89], v[96:97]
	v_pk_fma_f32 v[98:99], v[90:91], v[90:91], v[98:99]
	v_pk_fma_f32 v[96:97], v[84:85], v[84:85], v[96:97]
	v_pk_fma_f32 v[98:99], v[86:87], v[86:87], v[98:99]
	v_add_u32_e32 v145, 0x8000, v145
	v_add_f32_e32 v96, v96, v97
	v_add_f32_e32 v98, v98, v99
	v_add_f32_e32 v96, v96, v98
	s_waitcnt vmcnt(14)
	v_lshlrev_b32_e32 v236, 16, v188
	v_and_b32_e32 v237, 0xffff0000, v188
	v_lshlrev_b32_e32 v238, 16, v189
	v_and_b32_e32 v239, 0xffff0000, v189
	v_lshlrev_b32_e32 v188, 16, v190
	v_and_b32_e32 v189, 0xffff0000, v190
	v_lshlrev_b32_e32 v190, 16, v191
	v_and_b32_e32 v191, 0xffff0000, v191
	v_pk_add_f32 v[80:81], v[80:81], v[236:237]
	v_pk_add_f32 v[82:83], v[82:83], v[238:239]
	v_pk_add_f32 v[76:77], v[76:77], v[188:189]
	v_pk_add_f32 v[78:79], v[78:79], v[190:191]
	v_cvt_pk_bf16_f32 v188, v80, v81
	v_cvt_pk_bf16_f32 v189, v82, v83
	v_cvt_pk_bf16_f32 v190, v76, v77
	v_cvt_pk_bf16_f32 v191, v78, v79
	global_store_dwordx4 v145, v[188:191], s[6:7]
	v_pk_mul_f32 v[80:81], v[80:81], v[80:81]
	v_pk_mul_f32 v[82:83], v[82:83], v[82:83]
	v_pk_fma_f32 v[80:81], v[76:77], v[76:77], v[80:81]
	v_pk_fma_f32 v[82:83], v[78:79], v[78:79], v[82:83]
	v_lshlrev_b32_e32 v236, 16, v200
	v_and_b32_e32 v237, 0xffff0000, v200
	v_lshlrev_b32_e32 v238, 16, v201
	v_and_b32_e32 v239, 0xffff0000, v201
	v_lshlrev_b32_e32 v200, 16, v202
	v_and_b32_e32 v201, 0xffff0000, v202
	v_lshlrev_b32_e32 v202, 16, v203
	v_and_b32_e32 v203, 0xffff0000, v203
	v_pk_add_f32 v[72:73], v[72:73], v[236:237]
	v_pk_add_f32 v[74:75], v[74:75], v[238:239]
	v_pk_add_f32 v[68:69], v[68:69], v[200:201]
	v_pk_add_f32 v[70:71], v[70:71], v[202:203]
	v_cvt_pk_bf16_f32 v200, v72, v73
	v_cvt_pk_bf16_f32 v201, v74, v75
	v_cvt_pk_bf16_f32 v202, v68, v69
	v_cvt_pk_bf16_f32 v203, v70, v71
	global_store_dwordx4 v145, v[200:203], s[6:7] offset:256
	v_pk_fma_f32 v[80:81], v[72:73], v[72:73], v[80:81]
	v_pk_fma_f32 v[82:83], v[74:75], v[74:75], v[82:83]
	v_pk_fma_f32 v[80:81], v[68:69], v[68:69], v[80:81]
	v_pk_fma_f32 v[82:83], v[70:71], v[70:71], v[82:83]
	v_add_u32_e32 v145, 0x28000, v145
	v_add_f32_e32 v80, v80, v81
	v_add_f32_e32 v82, v82, v83
	v_add_f32_e32 v80, v80, v82
	s_waitcnt vmcnt(14)
	v_lshlrev_b32_e32 v236, 16, v204
	v_and_b32_e32 v237, 0xffff0000, v204
	v_lshlrev_b32_e32 v238, 16, v205
	v_and_b32_e32 v239, 0xffff0000, v205
	v_lshlrev_b32_e32 v204, 16, v206
	v_and_b32_e32 v205, 0xffff0000, v206
	v_lshlrev_b32_e32 v206, 16, v207
	v_and_b32_e32 v207, 0xffff0000, v207
	v_pk_add_f32 v[64:65], v[64:65], v[236:237]
	v_pk_add_f32 v[66:67], v[66:67], v[238:239]
	v_pk_add_f32 v[60:61], v[60:61], v[204:205]
	v_pk_add_f32 v[62:63], v[62:63], v[206:207]
	v_cvt_pk_bf16_f32 v204, v64, v65
	v_cvt_pk_bf16_f32 v205, v66, v67
	v_cvt_pk_bf16_f32 v206, v60, v61
	v_cvt_pk_bf16_f32 v207, v62, v63
	global_store_dwordx4 v145, v[204:207], s[6:7]
	v_pk_mul_f32 v[64:65], v[64:65], v[64:65]
	v_pk_mul_f32 v[66:67], v[66:67], v[66:67]
	v_pk_fma_f32 v[64:65], v[60:61], v[60:61], v[64:65]
	v_pk_fma_f32 v[66:67], v[62:63], v[62:63], v[66:67]
	v_lshlrev_b32_e32 v236, 16, v208
	v_and_b32_e32 v237, 0xffff0000, v208
	v_lshlrev_b32_e32 v238, 16, v209
	v_and_b32_e32 v239, 0xffff0000, v209
	v_lshlrev_b32_e32 v208, 16, v210
	v_and_b32_e32 v209, 0xffff0000, v210
	v_lshlrev_b32_e32 v210, 16, v211
	v_and_b32_e32 v211, 0xffff0000, v211
	v_pk_add_f32 v[56:57], v[56:57], v[236:237]
	v_pk_add_f32 v[58:59], v[58:59], v[238:239]
	v_pk_add_f32 v[52:53], v[52:53], v[208:209]
	v_pk_add_f32 v[54:55], v[54:55], v[210:211]
	v_cvt_pk_bf16_f32 v208, v56, v57
	v_cvt_pk_bf16_f32 v209, v58, v59
	v_cvt_pk_bf16_f32 v210, v52, v53
	v_cvt_pk_bf16_f32 v211, v54, v55
	global_store_dwordx4 v145, v[208:211], s[6:7] offset:256
	v_pk_fma_f32 v[64:65], v[56:57], v[56:57], v[64:65]
	v_pk_fma_f32 v[66:67], v[58:59], v[58:59], v[66:67]
	v_pk_fma_f32 v[64:65], v[52:53], v[52:53], v[64:65]
	v_pk_fma_f32 v[66:67], v[54:55], v[54:55], v[66:67]
	v_add_u32_e32 v145, 0x8000, v145
	v_add_f32_e32 v64, v64, v65
	v_add_f32_e32 v66, v66, v67
	v_add_f32_e32 v64, v64, v66
	s_waitcnt vmcnt(14)
	v_lshlrev_b32_e32 v236, 16, v212
	v_and_b32_e32 v237, 0xffff0000, v212
	v_lshlrev_b32_e32 v238, 16, v213
	v_and_b32_e32 v239, 0xffff0000, v213
	v_lshlrev_b32_e32 v212, 16, v214
	v_and_b32_e32 v213, 0xffff0000, v214
	v_lshlrev_b32_e32 v214, 16, v215
	v_and_b32_e32 v215, 0xffff0000, v215
	v_pk_add_f32 v[48:49], v[48:49], v[236:237]
	v_pk_add_f32 v[50:51], v[50:51], v[238:239]
	v_pk_add_f32 v[44:45], v[44:45], v[212:213]
	v_pk_add_f32 v[46:47], v[46:47], v[214:215]
	v_cvt_pk_bf16_f32 v212, v48, v49
	v_cvt_pk_bf16_f32 v213, v50, v51
	v_cvt_pk_bf16_f32 v214, v44, v45
	v_cvt_pk_bf16_f32 v215, v46, v47
	global_store_dwordx4 v145, v[212:215], s[6:7]
	v_pk_mul_f32 v[48:49], v[48:49], v[48:49]
	v_pk_mul_f32 v[50:51], v[50:51], v[50:51]
	v_pk_fma_f32 v[48:49], v[44:45], v[44:45], v[48:49]
	v_pk_fma_f32 v[50:51], v[46:47], v[46:47], v[50:51]
	v_lshlrev_b32_e32 v236, 16, v216
	v_and_b32_e32 v237, 0xffff0000, v216
	v_lshlrev_b32_e32 v238, 16, v217
	v_and_b32_e32 v239, 0xffff0000, v217
	v_lshlrev_b32_e32 v216, 16, v218
	v_and_b32_e32 v217, 0xffff0000, v218
	v_lshlrev_b32_e32 v218, 16, v219
	v_and_b32_e32 v219, 0xffff0000, v219
	v_pk_add_f32 v[40:41], v[40:41], v[236:237]
	v_pk_add_f32 v[42:43], v[42:43], v[238:239]
	v_pk_add_f32 v[36:37], v[36:37], v[216:217]
	v_pk_add_f32 v[38:39], v[38:39], v[218:219]
	v_cvt_pk_bf16_f32 v216, v40, v41
	v_cvt_pk_bf16_f32 v217, v42, v43
	v_cvt_pk_bf16_f32 v218, v36, v37
	v_cvt_pk_bf16_f32 v219, v38, v39
	global_store_dwordx4 v145, v[216:219], s[6:7] offset:256
	v_pk_fma_f32 v[48:49], v[40:41], v[40:41], v[48:49]
	v_pk_fma_f32 v[50:51], v[42:43], v[42:43], v[50:51]
	v_pk_fma_f32 v[48:49], v[36:37], v[36:37], v[48:49]
	v_pk_fma_f32 v[50:51], v[38:39], v[38:39], v[50:51]
	v_add_u32_e32 v145, 0x8000, v145
	v_add_f32_e32 v48, v48, v49
	v_add_f32_e32 v50, v50, v51
	v_add_f32_e32 v48, v48, v50
	s_waitcnt vmcnt(14)
	v_lshlrev_b32_e32 v236, 16, v220
	v_and_b32_e32 v237, 0xffff0000, v220
	v_lshlrev_b32_e32 v238, 16, v221
	v_and_b32_e32 v239, 0xffff0000, v221
	v_lshlrev_b32_e32 v220, 16, v222
	v_and_b32_e32 v221, 0xffff0000, v222
	v_lshlrev_b32_e32 v222, 16, v223
	v_and_b32_e32 v223, 0xffff0000, v223
	v_pk_add_f32 v[32:33], v[32:33], v[236:237]
	v_pk_add_f32 v[34:35], v[34:35], v[238:239]
	v_pk_add_f32 v[28:29], v[28:29], v[220:221]
	v_pk_add_f32 v[30:31], v[30:31], v[222:223]
	v_cvt_pk_bf16_f32 v220, v32, v33
	v_cvt_pk_bf16_f32 v221, v34, v35
	v_cvt_pk_bf16_f32 v222, v28, v29
	v_cvt_pk_bf16_f32 v223, v30, v31
	global_store_dwordx4 v145, v[220:223], s[6:7]
	v_pk_mul_f32 v[32:33], v[32:33], v[32:33]
	v_pk_mul_f32 v[34:35], v[34:35], v[34:35]
	v_pk_fma_f32 v[32:33], v[28:29], v[28:29], v[32:33]
	v_pk_fma_f32 v[34:35], v[30:31], v[30:31], v[34:35]
	v_lshlrev_b32_e32 v236, 16, v224
	v_and_b32_e32 v237, 0xffff0000, v224
	v_lshlrev_b32_e32 v238, 16, v225
	v_and_b32_e32 v239, 0xffff0000, v225
	v_lshlrev_b32_e32 v224, 16, v226
	v_and_b32_e32 v225, 0xffff0000, v226
	v_lshlrev_b32_e32 v226, 16, v227
	v_and_b32_e32 v227, 0xffff0000, v227
	v_pk_add_f32 v[24:25], v[24:25], v[236:237]
	v_pk_add_f32 v[26:27], v[26:27], v[238:239]
	v_pk_add_f32 v[20:21], v[20:21], v[224:225]
	v_pk_add_f32 v[22:23], v[22:23], v[226:227]
	v_cvt_pk_bf16_f32 v224, v24, v25
	v_cvt_pk_bf16_f32 v225, v26, v27
	v_cvt_pk_bf16_f32 v226, v20, v21
	v_cvt_pk_bf16_f32 v227, v22, v23
	global_store_dwordx4 v145, v[224:227], s[6:7] offset:256
	v_pk_fma_f32 v[32:33], v[24:25], v[24:25], v[32:33]
	v_pk_fma_f32 v[34:35], v[26:27], v[26:27], v[34:35]
	v_pk_fma_f32 v[32:33], v[20:21], v[20:21], v[32:33]
	v_pk_fma_f32 v[34:35], v[22:23], v[22:23], v[34:35]
	v_add_u32_e32 v145, 0x8000, v145
	v_add_f32_e32 v32, v32, v33
	v_add_f32_e32 v34, v34, v35
	v_add_f32_e32 v32, v32, v34
	s_waitcnt vmcnt(14)
	v_lshlrev_b32_e32 v236, 16, v228
	v_and_b32_e32 v237, 0xffff0000, v228
	v_lshlrev_b32_e32 v238, 16, v229
	v_and_b32_e32 v239, 0xffff0000, v229
	v_lshlrev_b32_e32 v228, 16, v230
	v_and_b32_e32 v229, 0xffff0000, v230
	v_lshlrev_b32_e32 v230, 16, v231
	v_and_b32_e32 v231, 0xffff0000, v231
	v_pk_add_f32 v[16:17], v[16:17], v[236:237]
	v_pk_add_f32 v[18:19], v[18:19], v[238:239]
	v_pk_add_f32 v[12:13], v[12:13], v[228:229]
	v_pk_add_f32 v[14:15], v[14:15], v[230:231]
	v_cvt_pk_bf16_f32 v228, v16, v17
	v_cvt_pk_bf16_f32 v229, v18, v19
	v_cvt_pk_bf16_f32 v230, v12, v13
	v_cvt_pk_bf16_f32 v231, v14, v15
	global_store_dwordx4 v145, v[228:231], s[6:7]
	v_pk_mul_f32 v[16:17], v[16:17], v[16:17]
	v_pk_mul_f32 v[18:19], v[18:19], v[18:19]
	v_pk_fma_f32 v[16:17], v[12:13], v[12:13], v[16:17]
	v_pk_fma_f32 v[18:19], v[14:15], v[14:15], v[18:19]
	v_lshlrev_b32_e32 v236, 16, v232
	v_and_b32_e32 v237, 0xffff0000, v232
	v_lshlrev_b32_e32 v238, 16, v233
	v_and_b32_e32 v239, 0xffff0000, v233
	v_lshlrev_b32_e32 v232, 16, v234
	v_and_b32_e32 v233, 0xffff0000, v234
	v_lshlrev_b32_e32 v234, 16, v235
	v_and_b32_e32 v235, 0xffff0000, v235
	v_pk_add_f32 v[8:9], v[8:9], v[236:237]
	v_pk_add_f32 v[10:11], v[10:11], v[238:239]
	v_pk_add_f32 v[4:5], v[4:5], v[232:233]
	v_pk_add_f32 v[6:7], v[6:7], v[234:235]
	v_cvt_pk_bf16_f32 v232, v8, v9
	v_cvt_pk_bf16_f32 v233, v10, v11
	v_cvt_pk_bf16_f32 v234, v4, v5
	v_cvt_pk_bf16_f32 v235, v6, v7
	global_store_dwordx4 v145, v[232:235], s[6:7] offset:256
	v_pk_fma_f32 v[16:17], v[8:9], v[8:9], v[16:17]
	v_pk_fma_f32 v[18:19], v[10:11], v[10:11], v[18:19]
	v_pk_fma_f32 v[16:17], v[4:5], v[4:5], v[16:17]
	v_pk_fma_f32 v[18:19], v[6:7], v[6:7], v[18:19]
	v_add_f32_e32 v16, v16, v17
	v_add_f32_e32 v18, v18, v19
	v_add_f32_e32 v16, v16, v18
	ds_bpermute_b32 v129, v155, v128
	ds_bpermute_b32 v113, v155, v112
	ds_bpermute_b32 v97, v155, v96
	ds_bpermute_b32 v81, v155, v80
	ds_bpermute_b32 v65, v155, v64
	ds_bpermute_b32 v49, v155, v48
	ds_bpermute_b32 v33, v155, v32
	ds_bpermute_b32 v17, v155, v16
	s_waitcnt lgkmcnt(0)
	v_add_f32_e32 v128, v128, v129
	v_add_f32_e32 v112, v112, v113
	v_add_f32_e32 v96, v96, v97
	v_add_f32_e32 v80, v80, v81
	v_add_f32_e32 v64, v64, v65
	v_add_f32_e32 v48, v48, v49
	v_add_f32_e32 v32, v32, v33
	v_add_f32_e32 v16, v16, v17
	ds_bpermute_b32 v129, v192, v128
	ds_bpermute_b32 v113, v192, v112
	ds_bpermute_b32 v97, v192, v96
	ds_bpermute_b32 v81, v192, v80
	ds_bpermute_b32 v65, v192, v64
	ds_bpermute_b32 v49, v192, v48
	ds_bpermute_b32 v33, v192, v32
	ds_bpermute_b32 v17, v192, v16
	s_waitcnt lgkmcnt(0)
	s_and_saveexec_b64 s[14:15], s[0:1]
	v_add_f32_e32 v128, v128, v129
	v_add_f32_e32 v112, v112, v113
	v_add_f32_e32 v96, v96, v97
	v_add_f32_e32 v80, v80, v81
	v_add_f32_e32 v64, v64, v65
	v_add_f32_e32 v48, v48, v49
	v_add_f32_e32 v32, v32, v33
	v_add_f32_e32 v16, v16, v17
	global_atomic_add_f32 v154, v128, s[8:9]
	global_atomic_add_f32 v154, v112, s[8:9] offset:64
	global_atomic_add_f32 v154, v96, s[8:9] offset:128
	global_atomic_add_f32 v154, v80, s[8:9] offset:192
	global_atomic_add_f32 v154, v64, s[8:9] offset:512
	global_atomic_add_f32 v154, v48, s[8:9] offset:576
	global_atomic_add_f32 v154, v32, s[8:9] offset:640
	global_atomic_add_f32 v154, v16, s[8:9] offset:704
